# ffn_down epilogue: residual loads batched (32 in flight) instead of load-wait-store per element
# speedup vs baseline: 1.0236x; 1.0236x over previous
; #define MFMA(a, b, c) __builtin_amdgcn_mfma_f32_32x32x16_bf16(a, b, c, 0, 0, 0)
; #define ISSUE(k0, bf) do { char* A_ = lw + (bf) * BUF; \
;     _Pragma("unroll") for (int i_ = 0; i_ < 4; ++i_) { glds16(al.ptr(lrow + 32 * i_, (k0) + cg), A_ + i_ * 4096); glds16(bl.ptr(lrow + 32 * i_, (k0) + cg), A_ + ABYTES + i_ * 4096); } \
;     if (HALO) { if (wid == 0) glds16(gh + (k0), A_ + 16384); } } while (0)
; template <bool HALO, class AL, class BL>
; __device__ __forceinline__ void gemm_core(f32x16 (&acc)[2][2], f32x16& hacc, const AL& al, const BL& bl, int K, char* lds,
;                                           const u16* halo0, const u16* halo1, int brow0, int brow1) {
;     ...
;   for (int kt = 0; kt < nk; ++kt) {
;     asm volatile("s_waitcnt vmcnt(0)" ::: "memory");
;     __syncthreads();
;     if (kt + 1 < nk) ISSUE((kt + 1) * 64, (kt + 1) & 1);
;     const char* T = lds + (kt & 1) * BUF;
; #pragma unroll
;     for (int kk = 0; kk < 4; ++kk) {
;       const int c = kk * 2 + hi;
;       bf16x8 a0 = *(const bf16x8*)(T + oa + ((c ^ sa) << 4));
;       bf16x8 a1 = *(const bf16x8*)(T + oa + 4096 + ((c ^ sa) << 4));
;       bf16x8 b0 = *(const bf16x8*)(T + ob0 + ((c ^ sb0) << 4));
;       bf16x8 b1 = *(const bf16x8*)(T + ob1 + ((c ^ sb1) << 4));
;       acc[0][0] = MFMA(a0, b0, acc[0][0]); acc[0][1] = MFMA(a0, b1, acc[0][1]);
;       acc[1][0] = MFMA(a1, b0, acc[1][0]); acc[1][1] = MFMA(a1, b1, acc[1][1]);
;       if (HALO) { bf16x8 ah = *(const bf16x8*)(T + oh + ((c ^ sh) << 4)); hacc = MFMA(ah, b0, hacc); }
;     }
;   }
.LBB0_156:
	s_add_i32 s3, s6, 0x8000
	s_and_b32 s7, s3, 0x8000
	v_add_u32_e32 v75, s7, v69
	v_lshl_add_u64 v[76:77], v[66:67], 0, s[80:81]
	s_mov_b64 s[18:19], 0xa0cff80
	v_readfirstlane_b32 s7, v75
	v_add_u32_e32 v82, 0x4000, v75
	v_lshl_add_u64 v[78:79], v[76:77], 0, s[18:19]
	s_mov_b32 m0, s7
	s_waitcnt vmcnt(0)
	s_waitcnt vmcnt(0) lgkmcnt(0)
	s_barrier
	global_load_lds_dwordx4 v[78:79], off
	v_lshl_add_u64 v[78:79], v[64:65], 0, s[80:81]
	s_mov_b64 s[18:19], 0x2500080
	v_readfirstlane_b32 s7, v82
	v_add_u32_e32 v82, 0x1000, v75
	v_lshl_add_u64 v[80:81], v[78:79], 0, s[18:19]
	s_mov_b32 m0, s7
	s_mov_b64 s[18:19], 0xa0fbf80
	v_readfirstlane_b32 s7, v82
	v_add_u32_e32 v82, 0x5000, v75
	global_load_lds_dwordx4 v[80:81], off
	v_lshl_add_u64 v[80:81], v[76:77], 0, s[18:19]
	s_mov_b32 m0, s7
	s_mov_b64 s[18:19], 0x252c080
	v_readfirstlane_b32 s7, v82
	v_add_u32_e32 v82, 0x2000, v75
	global_load_lds_dwordx4 v[80:81], off
	v_lshl_add_u64 v[80:81], v[78:79], 0, s[18:19]
	s_mov_b32 m0, s7
	s_mov_b64 s[18:19], 0xa127f80
	v_readfirstlane_b32 s7, v82
	v_add_u32_e32 v82, 0x6000, v75
	global_load_lds_dwordx4 v[80:81], off
	v_lshl_add_u64 v[80:81], v[76:77], 0, s[18:19]
	s_mov_b32 m0, s7
	s_mov_b64 s[18:19], 0x2558080
	v_readfirstlane_b32 s7, v82
	global_load_lds_dwordx4 v[80:81], off
	v_lshl_add_u64 v[80:81], v[78:79], 0, s[18:19]
	s_mov_b32 m0, s7
	s_mov_b64 s[18:19], 0xa153f80
	global_load_lds_dwordx4 v[80:81], off
	v_add_u32_e32 v80, 0x3000, v75
	v_add_u32_e32 v75, 0x7000, v75
	v_readfirstlane_b32 s7, v80
	v_lshl_add_u64 v[76:77], v[76:77], 0, s[18:19]
	s_mov_b32 m0, s7
	s_mov_b64 s[18:19], 0x2584080
	v_readfirstlane_b32 s7, v75
	global_load_lds_dwordx4 v[76:77], off
	v_lshl_add_u64 v[76:77], v[78:79], 0, s[18:19]
	s_mov_b32 m0, s7
	s_and_b32 s6, s6, 0x8000
	global_load_lds_dwordx4 v[76:77], off
	s_add_i32 s6, s6, 0
	v_add_u32_e32 v75, s6, v74
	v_add_u32_e32 v92, s6, v68
	v_add_u32_e32 v80, v75, v73
	v_add_u32_e32 v88, v92, v73
	ds_read_b128 v[76:79], v80
	ds_read_b128 v[80:83], v80 offset:4096
	ds_read_b128 v[84:87], v88 offset:16384
	ds_read_b128 v[88:91], v88 offset:20480
	s_waitcnt lgkmcnt(0)
	v_mfma_f32_32x32x16_bf16 v[48:63], v[76:79], v[84:87], v[48:63]
	s_add_u32 s80, s80, 0x80
	s_addc_u32 s81, s81, 0
	s_cmpk_lg_i32 s80, 0x1580
	s_mov_b32 s6, s3
	v_mfma_f32_32x32x16_bf16 v[32:47], v[76:79], v[88:91], v[32:47]
	v_mfma_f32_32x32x16_bf16 v[16:31], v[80:83], v[84:87], v[16:31]
	v_mfma_f32_32x32x16_bf16 v[0:15], v[80:83], v[88:91], v[0:15]
	v_add_u32_e32 v80, v75, v72
	v_add_u32_e32 v88, v92, v72
	ds_read_b128 v[76:79], v80
	ds_read_b128 v[80:83], v80 offset:4096
	ds_read_b128 v[84:87], v88 offset:16384
	ds_read_b128 v[88:91], v88 offset:20480
	s_waitcnt lgkmcnt(0)
	v_mfma_f32_32x32x16_bf16 v[48:63], v[76:79], v[84:87], v[48:63]
	v_mfma_f32_32x32x16_bf16 v[32:47], v[76:79], v[88:91], v[32:47]
	v_mfma_f32_32x32x16_bf16 v[16:31], v[80:83], v[84:87], v[16:31]
	v_mfma_f32_32x32x16_bf16 v[0:15], v[80:83], v[88:91], v[0:15]
	v_add_u32_e32 v80, v75, v71
	v_add_u32_e32 v88, v92, v71
	ds_read_b128 v[76:79], v80
	ds_read_b128 v[80:83], v80 offset:4096
	ds_read_b128 v[84:87], v88 offset:16384
	ds_read_b128 v[88:91], v88 offset:20480
	v_add_u32_e32 v75, v75, v70
	s_waitcnt lgkmcnt(0)
	v_mfma_f32_32x32x16_bf16 v[48:63], v[76:79], v[84:87], v[48:63]
	v_mfma_f32_32x32x16_bf16 v[32:47], v[76:79], v[88:91], v[32:47]
	v_mfma_f32_32x32x16_bf16 v[16:31], v[80:83], v[84:87], v[16:31]
	v_mfma_f32_32x32x16_bf16 v[0:15], v[80:83], v[88:91], v[0:15]
	ds_read_b128 v[76:79], v75
	ds_read_b128 v[80:83], v75 offset:4096
	v_add_u32_e32 v75, v92, v70
	ds_read_b128 v[84:87], v75 offset:16384
	ds_read_b128 v[88:91], v75 offset:20480
	s_waitcnt lgkmcnt(0)
	v_mfma_f32_32x32x16_bf16 v[48:63], v[76:79], v[84:87], v[48:63]
	v_mfma_f32_32x32x16_bf16 v[32:47], v[76:79], v[88:91], v[32:47]
	v_mfma_f32_32x32x16_bf16 v[16:31], v[80:83], v[84:87], v[16:31]
	v_mfma_f32_32x32x16_bf16 v[0:15], v[80:83], v[88:91], v[0:15]
	s_cbranch_scc1 .LBB0_156
	v_add_u32_e32 v69, 0, v74
	v_add_u32_e32 v68, 0, v68
	v_add_u32_e32 v74, v69, v73
	v_add_u32_e32 v73, v68, v73
	s_waitcnt vmcnt(0)
	s_waitcnt vmcnt(0)
	s_barrier
	ds_read_b128 v[64:67], v74 offset:32768
	ds_read_b128 v[74:77], v74 offset:36864
	ds_read_b128 v[78:81], v73 offset:49152
	ds_read_b128 v[82:85], v73 offset:53248
	s_waitcnt lgkmcnt(1)
	v_mfma_f32_32x32x16_bf16 v[48:63], v[64:67], v[78:81], v[48:63]
	v_add_u32_e32 v73, v69, v72
	v_add_u32_e32 v72, v68, v72
	s_waitcnt lgkmcnt(0)
	v_mfma_f32_32x32x16_bf16 v[32:47], v[64:67], v[82:85], v[32:47]
	v_mfma_f32_32x32x16_bf16 v[16:31], v[74:77], v[78:81], v[16:31]
	v_mfma_f32_32x32x16_bf16 v[0:15], v[74:77], v[82:85], v[0:15]
	ds_read_b128 v[64:67], v73 offset:32768
	ds_read_b128 v[74:77], v73 offset:36864
	ds_read_b128 v[78:81], v72 offset:49152
	ds_read_b128 v[82:85], v72 offset:53248
	v_add_u32_e32 v72, v69, v71
	v_add_u32_e32 v71, v68, v71
	v_add_u32_e32 v69, v69, v70
	s_waitcnt lgkmcnt(1)
	v_mfma_f32_32x32x16_bf16 v[48:63], v[64:67], v[78:81], v[48:63]
	s_waitcnt lgkmcnt(0)
	v_mfma_f32_32x32x16_bf16 v[32:47], v[64:67], v[82:85], v[32:47]
	v_mfma_f32_32x32x16_bf16 v[16:31], v[74:77], v[78:81], v[16:31]
	v_mfma_f32_32x32x16_bf16 v[0:15], v[74:77], v[82:85], v[0:15]
	ds_read_b128 v[64:67], v72 offset:32768
	ds_read_b128 v[72:75], v72 offset:36864
	ds_read_b128 v[76:79], v71 offset:49152
	ds_read_b128 v[80:83], v71 offset:53248
	s_waitcnt lgkmcnt(1)
	v_mfma_f32_32x32x16_bf16 v[48:63], v[64:67], v[76:79], v[48:63]
	s_waitcnt lgkmcnt(0)
; __device__ __forceinline__ float bf2f(u16 v) { return __uint_as_float(((unsigned)v) << 16); }
; __device__ __forceinline__ int opq() { int z = 0; asm volatile("" : "+v"(z)); return z; }
; #define SBAR() __builtin_amdgcn_sched_barrier(0)
; __device__ __forceinline__ void phase_ffn_down(const P& p, int layer, char* lds) {
;     ...
;     const unsigned rb = (unsigned)(tm * 128 + wr * 64 + 4 * hi + opq());
; #pragma unroll
;     for (int mi = 0; mi < 2; ++mi) {
; #pragma unroll
;       for (int ni = 0; ni < 2; ++ni)
; #pragma unroll
;         for (int r = 0; r < 16; ++r) {
;           const unsigned row = rb + mi * 32 + (r & 3) + 8 * (r >> 2); const unsigned col = tn * 128 + wc * 64 + ni * 32 + r32;
;           ((_Float16*)(p.ws + OFF_PRE2))[row * DM + col] = (_Float16)(ALPHA * bf2f(xb[row * DM + col]) + acc[mi][ni][r]);
;         }
;       SBAR();
;     }
	v_mfma_f32_32x32x16_bf16 v[32:47], v[64:67], v[80:83], v[32:47]
	v_mfma_f32_32x32x16_bf16 v[16:31], v[72:75], v[76:79], v[16:31]
	v_add_u32_e32 v76, v68, v70
	v_mfma_f32_32x32x16_bf16 v[0:15], v[72:75], v[80:83], v[0:15]
	ds_read_b128 v[64:67], v69 offset:32768
	ds_read_b128 v[72:75], v69 offset:36864
	ds_read_b128 v[68:71], v76 offset:49152
	ds_read_b128 v[76:79], v76 offset:53248
	s_waitcnt lgkmcnt(1)
	v_mfma_f32_32x32x16_bf16 v[48:63], v[64:67], v[68:71], v[48:63]
	s_waitcnt lgkmcnt(0)
	v_mfma_f32_32x32x16_bf16 v[32:47], v[64:67], v[76:79], v[32:47]
	v_mfma_f32_32x32x16_bf16 v[16:31], v[72:75], v[68:71], v[16:31]
	v_mfma_f32_32x32x16_bf16 v[0:15], v[72:75], v[76:79], v[0:15]
	v_lshl_add_u32 v67, s85, 7, v144
	v_lshl_or_b32 v65, s62, 7, v145
	v_lshlrev_b32_e32 v66, 10, v67
	v_add_lshl_u32 v64, v66, v65, 1
	global_load_ushort v80, v64, s[40:41]
	v_add_u32_e32 v65, 0x800, v64
	global_load_ushort v81, v65, s[40:41]
	v_add_u32_e32 v65, 0x1000, v64
	global_load_ushort v82, v65, s[40:41]
	v_add_u32_e32 v65, 0x1800, v64
	global_load_ushort v83, v65, s[40:41]
	v_add_u32_e32 v65, 0x4000, v64
	global_load_ushort v84, v65, s[40:41]
	v_add_u32_e32 v65, 0x4800, v64
	global_load_ushort v85, v65, s[40:41]
	v_add_u32_e32 v65, 0x5000, v64
	global_load_ushort v86, v65, s[40:41]
	v_add_u32_e32 v65, 0x5800, v64
	global_load_ushort v87, v65, s[40:41]
	v_add_u32_e32 v65, 0x8000, v64
	global_load_ushort v88, v65, s[40:41]
	v_add_u32_e32 v65, 0x8800, v64
	global_load_ushort v89, v65, s[40:41]
	v_add_u32_e32 v65, 0x9000, v64
	global_load_ushort v90, v65, s[40:41]
	v_add_u32_e32 v65, 0x9800, v64
	global_load_ushort v91, v65, s[40:41]
	v_add_u32_e32 v65, 0xc000, v64
	global_load_ushort v92, v65, s[40:41]
	v_add_u32_e32 v65, 0xc800, v64
	global_load_ushort v93, v65, s[40:41]
	v_add_u32_e32 v65, 0xd000, v64
	global_load_ushort v94, v65, s[40:41]
	v_add_u32_e32 v65, 0xd800, v64
	global_load_ushort v95, v65, s[40:41]
	v_add_u32_e32 v65, 0x40, v64
	global_load_ushort v96, v65, s[40:41]
	v_add_u32_e32 v65, 0x840, v64
	global_load_ushort v97, v65, s[40:41]
	v_add_u32_e32 v65, 0x1040, v64
	global_load_ushort v98, v65, s[40:41]
	v_add_u32_e32 v65, 0x1840, v64
	global_load_ushort v99, v65, s[40:41]
	v_add_u32_e32 v65, 0x4040, v64
	global_load_ushort v100, v65, s[40:41]
	v_add_u32_e32 v65, 0x4840, v64
	global_load_ushort v101, v65, s[40:41]
	v_add_u32_e32 v65, 0x5040, v64
	global_load_ushort v102, v65, s[40:41]
	v_add_u32_e32 v65, 0x5840, v64
	global_load_ushort v103, v65, s[40:41]
	v_add_u32_e32 v65, 0x8040, v64
	global_load_ushort v104, v65, s[40:41]
	v_add_u32_e32 v65, 0x8840, v64
	global_load_ushort v105, v65, s[40:41]
	v_add_u32_e32 v65, 0x9040, v64
	global_load_ushort v106, v65, s[40:41]
	v_add_u32_e32 v65, 0x9840, v64
	global_load_ushort v107, v65, s[40:41]
	v_add_u32_e32 v65, 0xc040, v64
	global_load_ushort v108, v65, s[40:41]
	v_add_u32_e32 v65, 0xc840, v64
	global_load_ushort v109, v65, s[40:41]
	v_add_u32_e32 v65, 0xd040, v64
	global_load_ushort v110, v65, s[40:41]
	v_add_u32_e32 v65, 0xd840, v64
	global_load_ushort v111, v65, s[40:41]
	s_waitcnt vmcnt(31)
	v_lshlrev_b32_e32 v80, 16, v80
	v_fma_mixlo_f16 v48, v80, s12, v48
	global_store_short v64, v48, s[60:61]
	v_add_u32_e32 v65, 0x10000, v64
	global_load_ushort v112, v65, s[40:41]
	s_waitcnt vmcnt(32)
	v_lshlrev_b32_e32 v81, 16, v81
	v_add_u32_e32 v65, 0x800, v64
	v_fma_mixlo_f16 v49, v81, s12, v49
	global_store_short v65, v49, s[60:61]
	v_add_u32_e32 v65, 0x10800, v64
	global_load_ushort v113, v65, s[40:41]
	s_waitcnt vmcnt(33)
	v_lshlrev_b32_e32 v82, 16, v82
	v_add_u32_e32 v65, 0x1000, v64
	v_fma_mixlo_f16 v50, v82, s12, v50
	global_store_short v65, v50, s[60:61]
	v_add_u32_e32 v65, 0x11000, v64
	global_load_ushort v114, v65, s[40:41]
	s_waitcnt vmcnt(34)
	v_lshlrev_b32_e32 v83, 16, v83
	v_add_u32_e32 v65, 0x1800, v64
	v_fma_mixlo_f16 v51, v83, s12, v51
	global_store_short v65, v51, s[60:61]
	v_add_u32_e32 v65, 0x11800, v64
	global_load_ushort v115, v65, s[40:41]
	s_waitcnt vmcnt(35)
	v_lshlrev_b32_e32 v84, 16, v84
	v_add_u32_e32 v65, 0x4000, v64
	v_fma_mixlo_f16 v52, v84, s12, v52
	global_store_short v65, v52, s[60:61]
	v_add_u32_e32 v65, 0x14000, v64
	global_load_ushort v116, v65, s[40:41]
	s_waitcnt vmcnt(36)
	v_lshlrev_b32_e32 v85, 16, v85
	v_add_u32_e32 v65, 0x4800, v64
	v_fma_mixlo_f16 v53, v85, s12, v53
	global_store_short v65, v53, s[60:61]
	v_add_u32_e32 v65, 0x14800, v64
	global_load_ushort v117, v65, s[40:41]
	s_waitcnt vmcnt(37)
	v_lshlrev_b32_e32 v86, 16, v86
	v_add_u32_e32 v65, 0x5000, v64
	v_fma_mixlo_f16 v54, v86, s12, v54
	global_store_short v65, v54, s[60:61]
	v_add_u32_e32 v65, 0x15000, v64
	global_load_ushort v118, v65, s[40:41]
	s_waitcnt vmcnt(38)
	v_lshlrev_b32_e32 v87, 16, v87
	v_add_u32_e32 v65, 0x5800, v64
	v_fma_mixlo_f16 v55, v87, s12, v55
	global_store_short v65, v55, s[60:61]
	v_add_u32_e32 v65, 0x15800, v64
	global_load_ushort v119, v65, s[40:41]
	s_waitcnt vmcnt(39)
	v_lshlrev_b32_e32 v88, 16, v88
	v_add_u32_e32 v65, 0x8000, v64
	v_fma_mixlo_f16 v56, v88, s12, v56
	global_store_short v65, v56, s[60:61]
	v_add_u32_e32 v65, 0x18000, v64
	global_load_ushort v120, v65, s[40:41]
	s_waitcnt vmcnt(40)
	v_lshlrev_b32_e32 v89, 16, v89
	v_add_u32_e32 v65, 0x8800, v64
	v_fma_mixlo_f16 v57, v89, s12, v57
	global_store_short v65, v57, s[60:61]
	v_add_u32_e32 v65, 0x18800, v64
	global_load_ushort v121, v65, s[40:41]
	s_waitcnt vmcnt(41)
	v_lshlrev_b32_e32 v90, 16, v90
	v_add_u32_e32 v65, 0x9000, v64
	v_fma_mixlo_f16 v58, v90, s12, v58
	global_store_short v65, v58, s[60:61]
	v_add_u32_e32 v65, 0x19000, v64
	global_load_ushort v122, v65, s[40:41]
	s_waitcnt vmcnt(42)
; __device__ __forceinline__ float bf2f(u16 v) { return __uint_as_float(((unsigned)v) << 16); }
; #define SBAR() __builtin_amdgcn_sched_barrier(0)
; __device__ __forceinline__ void phase_ffn_down(const P& p, int layer, char* lds) {
;     ...
;     for (int mi = 0; mi < 2; ++mi) {
; #pragma unroll
;       for (int ni = 0; ni < 2; ++ni)
; #pragma unroll
;         for (int r = 0; r < 16; ++r) {
;           const unsigned row = rb + mi * 32 + (r & 3) + 8 * (r >> 2); const unsigned col = tn * 128 + wc * 64 + ni * 32 + r32;
;           ((_Float16*)(p.ws + OFF_PRE2))[row * DM + col] = (_Float16)(ALPHA * bf2f(xb[row * DM + col]) + acc[mi][ni][r]);
;         }
;       SBAR();
;     }
	v_lshlrev_b32_e32 v91, 16, v91
	v_add_u32_e32 v65, 0x9800, v64
	v_fma_mixlo_f16 v59, v91, s12, v59
	global_store_short v65, v59, s[60:61]
	v_add_u32_e32 v65, 0x19800, v64
	global_load_ushort v123, v65, s[40:41]
	s_waitcnt vmcnt(43)
	v_lshlrev_b32_e32 v92, 16, v92
	v_add_u32_e32 v65, 0xc000, v64
	v_fma_mixlo_f16 v60, v92, s12, v60
	global_store_short v65, v60, s[60:61]
	v_add_u32_e32 v65, 0x1c000, v64
	global_load_ushort v124, v65, s[40:41]
	s_waitcnt vmcnt(44)
	v_lshlrev_b32_e32 v93, 16, v93
	v_add_u32_e32 v65, 0xc800, v64
	v_fma_mixlo_f16 v61, v93, s12, v61
	global_store_short v65, v61, s[60:61]
	v_add_u32_e32 v65, 0x1c800, v64
	global_load_ushort v125, v65, s[40:41]
	s_waitcnt vmcnt(45)
	v_lshlrev_b32_e32 v94, 16, v94
	v_add_u32_e32 v65, 0xd000, v64
	v_fma_mixlo_f16 v62, v94, s12, v62
	global_store_short v65, v62, s[60:61]
	v_add_u32_e32 v65, 0x1d000, v64
	global_load_ushort v126, v65, s[40:41]
	s_waitcnt vmcnt(46)
	v_lshlrev_b32_e32 v95, 16, v95
	v_add_u32_e32 v65, 0xd800, v64
	v_fma_mixlo_f16 v63, v95, s12, v63
	global_store_short v65, v63, s[60:61]
	v_add_u32_e32 v65, 0x1d800, v64
	global_load_ushort v127, v65, s[40:41]
	s_waitcnt vmcnt(47)
	v_lshlrev_b32_e32 v96, 16, v96
	v_add_u32_e32 v65, 0x40, v64
	v_fma_mixlo_f16 v32, v96, s12, v32
	global_store_short v65, v32, s[60:61]
	v_add_u32_e32 v65, 0x10040, v64
	global_load_ushort v128, v65, s[40:41]
	s_waitcnt vmcnt(48)
	v_lshlrev_b32_e32 v97, 16, v97
	v_add_u32_e32 v65, 0x840, v64
	v_fma_mixlo_f16 v33, v97, s12, v33
	global_store_short v65, v33, s[60:61]
	v_add_u32_e32 v65, 0x10840, v64
	global_load_ushort v129, v65, s[40:41]
	s_waitcnt vmcnt(49)
	v_lshlrev_b32_e32 v98, 16, v98
	v_add_u32_e32 v65, 0x1040, v64
	v_fma_mixlo_f16 v34, v98, s12, v34
	global_store_short v65, v34, s[60:61]
	v_add_u32_e32 v65, 0x11040, v64
	global_load_ushort v130, v65, s[40:41]
	s_waitcnt vmcnt(50)
	v_lshlrev_b32_e32 v99, 16, v99
	v_add_u32_e32 v65, 0x1840, v64
	v_fma_mixlo_f16 v35, v99, s12, v35
	global_store_short v65, v35, s[60:61]
	v_add_u32_e32 v65, 0x11840, v64
	global_load_ushort v131, v65, s[40:41]
	s_waitcnt vmcnt(51)
	v_lshlrev_b32_e32 v100, 16, v100
	v_add_u32_e32 v65, 0x4040, v64
	v_fma_mixlo_f16 v36, v100, s12, v36
	global_store_short v65, v36, s[60:61]
	v_add_u32_e32 v65, 0x14040, v64
	global_load_ushort v132, v65, s[40:41]
	s_waitcnt vmcnt(52)
	v_lshlrev_b32_e32 v101, 16, v101
	v_add_u32_e32 v65, 0x4840, v64
	v_fma_mixlo_f16 v37, v101, s12, v37
	global_store_short v65, v37, s[60:61]
	v_add_u32_e32 v65, 0x14840, v64
	global_load_ushort v133, v65, s[40:41]
	s_waitcnt vmcnt(53)
	v_lshlrev_b32_e32 v102, 16, v102
	v_add_u32_e32 v65, 0x5040, v64
	v_fma_mixlo_f16 v38, v102, s12, v38
	global_store_short v65, v38, s[60:61]
	v_add_u32_e32 v65, 0x15040, v64
	global_load_ushort v134, v65, s[40:41]
	s_waitcnt vmcnt(54)
	v_lshlrev_b32_e32 v103, 16, v103
	v_add_u32_e32 v65, 0x5840, v64
	v_fma_mixlo_f16 v39, v103, s12, v39
	global_store_short v65, v39, s[60:61]
	v_add_u32_e32 v65, 0x15840, v64
	global_load_ushort v135, v65, s[40:41]
	s_waitcnt vmcnt(55)
	v_lshlrev_b32_e32 v104, 16, v104
	v_add_u32_e32 v65, 0x8040, v64
	v_fma_mixlo_f16 v40, v104, s12, v40
	global_store_short v65, v40, s[60:61]
	v_add_u32_e32 v65, 0x18040, v64
	global_load_ushort v136, v65, s[40:41]
	s_waitcnt vmcnt(56)
	v_lshlrev_b32_e32 v105, 16, v105
	v_add_u32_e32 v65, 0x8840, v64
	v_fma_mixlo_f16 v41, v105, s12, v41
	global_store_short v65, v41, s[60:61]
	v_add_u32_e32 v65, 0x18840, v64
	global_load_ushort v137, v65, s[40:41]
	s_waitcnt vmcnt(57)
	v_lshlrev_b32_e32 v106, 16, v106
	v_add_u32_e32 v65, 0x9040, v64
	v_fma_mixlo_f16 v42, v106, s12, v42
	global_store_short v65, v42, s[60:61]
	v_add_u32_e32 v65, 0x19040, v64
	global_load_ushort v138, v65, s[40:41]
	s_waitcnt vmcnt(58)
	v_lshlrev_b32_e32 v107, 16, v107
	v_add_u32_e32 v65, 0x9840, v64
	v_fma_mixlo_f16 v43, v107, s12, v43
	global_store_short v65, v43, s[60:61]
	v_add_u32_e32 v65, 0x19840, v64
	global_load_ushort v139, v65, s[40:41]
	s_waitcnt vmcnt(59)
	v_lshlrev_b32_e32 v108, 16, v108
	v_add_u32_e32 v65, 0xc040, v64
	v_fma_mixlo_f16 v44, v108, s12, v44
	global_store_short v65, v44, s[60:61]
	v_add_u32_e32 v65, 0x1c040, v64
	global_load_ushort v140, v65, s[40:41]
	s_waitcnt vmcnt(60)
	v_lshlrev_b32_e32 v109, 16, v109
	v_add_u32_e32 v65, 0xc840, v64
	v_fma_mixlo_f16 v45, v109, s12, v45
	global_store_short v65, v45, s[60:61]
	v_add_u32_e32 v65, 0x1c840, v64
	global_load_ushort v141, v65, s[40:41]
	s_waitcnt vmcnt(61)
	v_lshlrev_b32_e32 v110, 16, v110
	v_add_u32_e32 v65, 0xd040, v64
	v_fma_mixlo_f16 v46, v110, s12, v46
	global_store_short v65, v46, s[60:61]
	v_add_u32_e32 v65, 0x1d040, v64
	global_load_ushort v142, v65, s[40:41]
	s_waitcnt vmcnt(62)
	v_lshlrev_b32_e32 v111, 16, v111
	v_add_u32_e32 v65, 0xd840, v64
	v_fma_mixlo_f16 v47, v111, s12, v47
	global_store_short v65, v47, s[60:61]
	v_add_u32_e32 v65, 0x1d840, v64
	global_load_ushort v143, v65, s[40:41]
	s_waitcnt vmcnt(62)
	v_lshlrev_b32_e32 v112, 16, v112
	v_add_u32_e32 v65, 0x10000, v64
	v_fma_mixlo_f16 v16, v112, s12, v16
	global_store_short v65, v16, s[60:61]
	s_waitcnt vmcnt(61)
; __device__ __forceinline__ float bf2f(u16 v) { return __uint_as_float(((unsigned)v) << 16); }
; __device__ __forceinline__ int opq() { int z = 0; asm volatile("" : "+v"(z)); return z; }
; #define SBAR() __builtin_amdgcn_sched_barrier(0)
; __device__ __forceinline__ void phase_ffn_down(const P& p, int layer, char* lds) {
;     ...
;   for (int it = 0; tile_at(it, 256, 8, tm, tn); ++it) {
;     ...
;     const unsigned rb = (unsigned)(tm * 128 + wr * 64 + 4 * hi + opq());
; #pragma unroll
;     for (int mi = 0; mi < 2; ++mi) {
; #pragma unroll
;       for (int ni = 0; ni < 2; ++ni)
; #pragma unroll
;         for (int r = 0; r < 16; ++r) {
;           const unsigned row = rb + mi * 32 + (r & 3) + 8 * (r >> 2); const unsigned col = tn * 128 + wc * 64 + ni * 32 + r32;
;           ((_Float16*)(p.ws + OFF_PRE2))[row * DM + col] = (_Float16)(ALPHA * bf2f(xb[row * DM + col]) + acc[mi][ni][r]);
;         }
;       SBAR();
;     }
	v_lshlrev_b32_e32 v113, 16, v113
	v_add_u32_e32 v65, 0x10800, v64
	v_fma_mixlo_f16 v17, v113, s12, v17
	global_store_short v65, v17, s[60:61]
	s_waitcnt vmcnt(60)
	v_lshlrev_b32_e32 v114, 16, v114
	v_add_u32_e32 v65, 0x11000, v64
	v_fma_mixlo_f16 v18, v114, s12, v18
	global_store_short v65, v18, s[60:61]
	s_waitcnt vmcnt(59)
	v_lshlrev_b32_e32 v115, 16, v115
	v_add_u32_e32 v65, 0x11800, v64
	v_fma_mixlo_f16 v19, v115, s12, v19
	global_store_short v65, v19, s[60:61]
	s_waitcnt vmcnt(58)
	v_lshlrev_b32_e32 v116, 16, v116
	v_add_u32_e32 v65, 0x14000, v64
	v_fma_mixlo_f16 v20, v116, s12, v20
	global_store_short v65, v20, s[60:61]
	s_waitcnt vmcnt(57)
	v_lshlrev_b32_e32 v117, 16, v117
	v_add_u32_e32 v65, 0x14800, v64
	v_fma_mixlo_f16 v21, v117, s12, v21
	global_store_short v65, v21, s[60:61]
	s_waitcnt vmcnt(56)
	v_lshlrev_b32_e32 v118, 16, v118
	v_add_u32_e32 v65, 0x15000, v64
	v_fma_mixlo_f16 v22, v118, s12, v22
	global_store_short v65, v22, s[60:61]
	s_waitcnt vmcnt(55)
	v_lshlrev_b32_e32 v119, 16, v119
	v_add_u32_e32 v65, 0x15800, v64
	v_fma_mixlo_f16 v23, v119, s12, v23
	global_store_short v65, v23, s[60:61]
	s_waitcnt vmcnt(54)
	v_lshlrev_b32_e32 v120, 16, v120
	v_add_u32_e32 v65, 0x18000, v64
	v_fma_mixlo_f16 v24, v120, s12, v24
	global_store_short v65, v24, s[60:61]
	s_waitcnt vmcnt(53)
	v_lshlrev_b32_e32 v121, 16, v121
	v_add_u32_e32 v65, 0x18800, v64
	v_fma_mixlo_f16 v25, v121, s12, v25
	global_store_short v65, v25, s[60:61]
	s_waitcnt vmcnt(52)
	v_lshlrev_b32_e32 v122, 16, v122
	v_add_u32_e32 v65, 0x19000, v64
	v_fma_mixlo_f16 v26, v122, s12, v26
	global_store_short v65, v26, s[60:61]
	s_waitcnt vmcnt(51)
	v_lshlrev_b32_e32 v123, 16, v123
	v_add_u32_e32 v65, 0x19800, v64
	v_fma_mixlo_f16 v27, v123, s12, v27
	global_store_short v65, v27, s[60:61]
	s_waitcnt vmcnt(50)
	v_lshlrev_b32_e32 v124, 16, v124
	v_add_u32_e32 v65, 0x1c000, v64
	v_fma_mixlo_f16 v28, v124, s12, v28
	global_store_short v65, v28, s[60:61]
	s_waitcnt vmcnt(49)
	v_lshlrev_b32_e32 v125, 16, v125
	v_add_u32_e32 v65, 0x1c800, v64
	v_fma_mixlo_f16 v29, v125, s12, v29
	global_store_short v65, v29, s[60:61]
	s_waitcnt vmcnt(48)
	v_lshlrev_b32_e32 v126, 16, v126
	v_add_u32_e32 v65, 0x1d000, v64
	v_fma_mixlo_f16 v30, v126, s12, v30
	global_store_short v65, v30, s[60:61]
	s_waitcnt vmcnt(47)
	v_lshlrev_b32_e32 v127, 16, v127
	v_add_u32_e32 v65, 0x1d800, v64
	v_fma_mixlo_f16 v31, v127, s12, v31
	global_store_short v65, v31, s[60:61]
	s_waitcnt vmcnt(46)
	v_lshlrev_b32_e32 v128, 16, v128
	v_add_u32_e32 v65, 0x10040, v64
	v_fma_mixlo_f16 v0, v128, s12, v0
	global_store_short v65, v0, s[60:61]
	s_waitcnt vmcnt(45)
	v_lshlrev_b32_e32 v129, 16, v129
	v_add_u32_e32 v65, 0x10840, v64
	v_fma_mixlo_f16 v1, v129, s12, v1
	global_store_short v65, v1, s[60:61]
	s_waitcnt vmcnt(44)
	v_lshlrev_b32_e32 v130, 16, v130
	v_add_u32_e32 v65, 0x11040, v64
	v_fma_mixlo_f16 v2, v130, s12, v2
	global_store_short v65, v2, s[60:61]
	s_waitcnt vmcnt(43)
	v_lshlrev_b32_e32 v131, 16, v131
	v_add_u32_e32 v65, 0x11840, v64
	v_fma_mixlo_f16 v3, v131, s12, v3
	global_store_short v65, v3, s[60:61]
	s_waitcnt vmcnt(42)
	v_lshlrev_b32_e32 v132, 16, v132
	v_add_u32_e32 v65, 0x14040, v64
	v_fma_mixlo_f16 v4, v132, s12, v4
	global_store_short v65, v4, s[60:61]
	s_waitcnt vmcnt(41)
	v_lshlrev_b32_e32 v133, 16, v133
	v_add_u32_e32 v65, 0x14840, v64
	v_fma_mixlo_f16 v5, v133, s12, v5
	global_store_short v65, v5, s[60:61]
	s_waitcnt vmcnt(40)
	v_lshlrev_b32_e32 v134, 16, v134
	v_add_u32_e32 v65, 0x15040, v64
	v_fma_mixlo_f16 v6, v134, s12, v6
	global_store_short v65, v6, s[60:61]
	s_waitcnt vmcnt(39)
	v_lshlrev_b32_e32 v135, 16, v135
	v_add_u32_e32 v65, 0x15840, v64
	v_fma_mixlo_f16 v7, v135, s12, v7
	global_store_short v65, v7, s[60:61]
	s_waitcnt vmcnt(38)
	v_lshlrev_b32_e32 v136, 16, v136
	v_add_u32_e32 v65, 0x18040, v64
	v_fma_mixlo_f16 v8, v136, s12, v8
	global_store_short v65, v8, s[60:61]
	s_waitcnt vmcnt(37)
	v_lshlrev_b32_e32 v137, 16, v137
	v_add_u32_e32 v65, 0x18840, v64
	v_fma_mixlo_f16 v9, v137, s12, v9
	global_store_short v65, v9, s[60:61]
	s_waitcnt vmcnt(36)
	v_lshlrev_b32_e32 v138, 16, v138
	v_add_u32_e32 v65, 0x19040, v64
	v_fma_mixlo_f16 v10, v138, s12, v10
	global_store_short v65, v10, s[60:61]
	s_waitcnt vmcnt(35)
	v_lshlrev_b32_e32 v139, 16, v139
	v_add_u32_e32 v65, 0x19840, v64
	v_fma_mixlo_f16 v11, v139, s12, v11
	global_store_short v65, v11, s[60:61]
	s_waitcnt vmcnt(34)
	v_lshlrev_b32_e32 v140, 16, v140
	v_add_u32_e32 v65, 0x1c040, v64
	v_fma_mixlo_f16 v12, v140, s12, v12
	global_store_short v65, v12, s[60:61]
	s_waitcnt vmcnt(33)
	v_lshlrev_b32_e32 v141, 16, v141
	v_add_u32_e32 v65, 0x1c840, v64
	v_fma_mixlo_f16 v13, v141, s12, v13
	global_store_short v65, v13, s[60:61]
	s_waitcnt vmcnt(32)
	v_lshlrev_b32_e32 v142, 16, v142
	v_add_u32_e32 v65, 0x1d040, v64
	v_fma_mixlo_f16 v14, v142, s12, v14
	global_store_short v65, v14, s[60:61]
	s_waitcnt vmcnt(31)
	v_lshlrev_b32_e32 v143, 16, v143
	v_add_u32_e32 v65, 0x1d840, v64
	v_fma_mixlo_f16 v15, v143, s12, v15
	global_store_short v65, v15, s[60:61]
	s_add_i32 s84, s84, 1
	v_readlane_b32 s3, v255, 25
	s_mul_i32 s3, s84, s3
	s_add_i32 s80, s3, s13
	s_cmpk_gt_u32 s80, 0xff
	s_cbranch_scc0 .LBB0_155
